# v57 + SSD step 4 (gating, D*x skip, sum of squares) regenerated with packed f32 math, symbolically verified identical dataflow
# speedup vs baseline: 1.0133x; 1.0133x over previous
; __device__ __forceinline__ void phase_ssd(const Params& p, uchar* sm, int j, bf16_t* zx, const float* dtraw, float* ssqb) {
;     ...
;             __syncthreads();
; #pragma unroll
;             for (int m = 0; m < 4; ++m)
; #pragma unroll
;                 for (int r = 0; r < 4; ++r) *(float*)(sm + (m * 16 + quad * 4 + r) * RS_Y + (chl + l15) * 4) = yacc[m][r];
;             __syncthreads();
.LBB0_479:
	v_add_u32_e32 v104, 0x400, v224
	s_barrier
	ds_write2_b32 v104, v110, v111 offset0:8 offset1:140
	v_add_u32_e32 v104, 0x2000, v224
	ds_write2_b32 v104, v112, v113 offset0:64 offset1:196
	v_add_u32_e32 v104, 0x2400, v224
	ds_write2_b32 v104, v114, v115 offset0:72 offset1:204
	v_add_u32_e32 v104, 0x4200, v224
	ds_write2_b32 v104, v120, v121 offset1:132
	v_add_u32_e32 v104, 0x4600, v224
	ds_write2_b32 v104, v122, v123 offset0:8 offset1:140
	v_add_u32_e32 v104, 0x6200, v224
	ds_write2_b32 v104, v116, v117 offset0:64 offset1:196
	v_add_u32_e32 v104, 0x6600, v224
	s_waitcnt vmcnt(11)
	ds_write2_b32 v104, v118, v119 offset0:72 offset1:204
	ds_write2_b32 v224, v108, v109 offset1:132
	s_waitcnt lgkmcnt(0)
	s_barrier
; __device__ __forceinline__ u32x4 pack8(const float (&o)[8]) { u32x4 r; r.x = pk2(o[0], o[1]); r.y = pk2(o[2], o[3]); r.z = pk2(o[4], o[5]); r.w = pk2(o[6], o[7]); return r; }
; __device__ __forceinline__ float silu_f(float v) { return v * __builtin_amdgcn_rcpf(1.f + __expf(-v)); }
; __device__ __forceinline__ void phase_ssd(const Params& p, uchar* sm, int j, bf16_t* zx, const float* dtraw, float* ssqb) {
;     ...
;             {
;                 float zf[8], o[8], xf[8];
;                 const f32x4 y0 = *(const f32x4*)(sm + (2 * lp) * RS_Y + c8 * 32), y1 = *(const f32x4*)(sm + (2 * lp) * RS_Y + c8 * 32 + 16);
;                 unpack8(z0, zf); unpack8(xp0, xf);
; #pragma unroll
;                 for (int i = 0; i < 4; ++i) { o[i] = (y0[i] + dskip * xf[i]) * silu_f(zf[i]); o[4 + i] = (y1[i] + dskip * xf[4 + i]) * silu_f(zf[4 + i]); }
;                 *(u32x4*)(zc + colx + toff) = pack8(o);
;                 float q0 = 0.f;
; #pragma unroll
;                 for (int i = 0; i < 8; ++i) q0 += o[i] * o[i];
;                 const f32x4 y2 = *(const f32x4*)(sm + (2 * lp + 1) * RS_Y + c8 * 32), y3 = *(const f32x4*)(sm + (2 * lp + 1) * RS_Y + c8 * 32 + 16);
;                 unpack8(z1, zf); unpack8(xp1, xf);
; #pragma unroll
;                 for (int i = 0; i < 4; ++i) { o[i] = (y2[i] + dskip * xf[i]) * silu_f(zf[i]); o[4 + i] = (y3[i] + dskip * xf[4 + i]) * silu_f(zf[4 + i]); }
;                 *(u32x4*)(zc + colx + LDZ + toff) = pack8(o);
;                 float q1 = 0.f;
; #pragma unroll
;                 for (int i = 0; i < 8; ++i) q1 += o[i] * o[i];
; #pragma unroll
;                 for (int sft = 1; sft < 16; sft <<= 1) { q0 += __shfl_xor(q0, sft); q1 += __shfl_xor(q1, sft); }
;                 if (c8 == 0) { float* sq = ssqb + (size_t)(zrow0 + 2 * lp) * 16 + g * 2 + hp; sq[0] = q0; sq[16] = q1; }
	ds_read_b128 v[104:107], v225
	ds_read_b128 v[108:111], v225 offset:16
	ds_read_b128 v[124:127], v226
	ds_read_b128 v[128:131], v226 offset:16
	v_lshlrev_b32_e32 v132, 16, v100
	v_and_b32_e32 v133, 0xffff0000, v100
	v_lshlrev_b32_e32 v134, 16, v101
	v_and_b32_e32 v135, 0xffff0000, v101
	v_lshlrev_b32_e32 v238, 16, v102
	v_and_b32_e32 v239, 0xffff0000, v102
	v_lshlrev_b32_e32 v240, 16, v103
	v_and_b32_e32 v241, 0xffff0000, v103
	v_pk_mul_f32 v[112:113], v[132:133], s[98:99]
	v_pk_mul_f32 v[114:115], v[134:135], s[98:99]
	v_pk_mul_f32 v[116:117], v[238:239], s[98:99]
	v_pk_mul_f32 v[118:119], v[240:241], s[98:99]
	v_exp_f32_e32 v112, v112
	v_exp_f32_e32 v113, v113
	v_exp_f32_e32 v114, v114
	v_exp_f32_e32 v115, v115
	v_exp_f32_e32 v116, v116
	v_exp_f32_e32 v117, v117
	v_exp_f32_e32 v118, v118
	v_exp_f32_e32 v119, v119
	v_pk_add_f32 v[112:113], v[112:113], s[100:101]
	v_pk_add_f32 v[114:115], v[114:115], s[100:101]
	v_pk_add_f32 v[116:117], v[116:117], s[100:101]
	v_pk_add_f32 v[118:119], v[118:119], s[100:101]
	v_rcp_f32_e32 v112, v112
	v_rcp_f32_e32 v113, v113
	v_rcp_f32_e32 v114, v114
	v_rcp_f32_e32 v115, v115
	v_rcp_f32_e32 v116, v116
	v_rcp_f32_e32 v117, v117
	v_rcp_f32_e32 v118, v118
	v_rcp_f32_e32 v119, v119
	v_pk_mul_f32 v[112:113], v[112:113], v[132:133]
	v_pk_mul_f32 v[114:115], v[114:115], v[134:135]
	v_pk_mul_f32 v[116:117], v[116:117], v[238:239]
	v_pk_mul_f32 v[118:119], v[118:119], v[240:241]
	v_lshlrev_b32_e32 v132, 16, v235
	v_and_b32_e32 v133, 0xffff0000, v235
	v_lshlrev_b32_e32 v134, 16, v233
	v_and_b32_e32 v135, 0xffff0000, v233
	v_lshlrev_b32_e32 v238, 16, v236
	v_and_b32_e32 v239, 0xffff0000, v236
	v_lshlrev_b32_e32 v240, 16, v234
	v_and_b32_e32 v241, 0xffff0000, v234
	v_pk_mul_f32 v[132:133], v[132:133], v[170:171] op_sel:[0,1] op_sel_hi:[1,1]
	v_pk_mul_f32 v[134:135], v[134:135], v[170:171] op_sel:[0,1] op_sel_hi:[1,1]
	v_pk_mul_f32 v[238:239], v[238:239], v[170:171] op_sel:[0,1] op_sel_hi:[1,1]
	v_pk_mul_f32 v[240:241], v[240:241], v[170:171] op_sel:[0,1] op_sel_hi:[1,1]
	s_waitcnt lgkmcnt(2)
	v_pk_add_f32 v[132:133], v[132:133], v[104:105]
	v_pk_add_f32 v[134:135], v[134:135], v[106:107]
	v_pk_add_f32 v[238:239], v[238:239], v[108:109]
	v_pk_add_f32 v[240:241], v[240:241], v[110:111]
	v_pk_mul_f32 v[112:113], v[112:113], v[132:133]
	v_pk_mul_f32 v[114:115], v[114:115], v[134:135]
	v_pk_mul_f32 v[116:117], v[116:117], v[238:239]
	v_pk_mul_f32 v[118:119], v[118:119], v[240:241]
	v_mul_f32_e32 v120, v113, v113
	v_fmac_f32_e32 v120, v112, v112
	v_fmac_f32_e32 v120, v114, v114
	v_fmac_f32_e32 v120, v115, v115
	v_fmac_f32_e32 v120, v116, v116
	v_fmac_f32_e32 v120, v117, v117
	v_fmac_f32_e32 v120, v118, v118
	v_fmac_f32_e32 v120, v119, v119
	s_waitcnt vmcnt(10)
	v_lshlrev_b32_e32 v242, 16, v96
	v_and_b32_e32 v243, 0xffff0000, v96
	v_lshlrev_b32_e32 v246, 16, v97
	v_and_b32_e32 v247, 0xffff0000, v97
	v_lshlrev_b32_e32 v248, 16, v98
	v_and_b32_e32 v249, 0xffff0000, v98
	v_lshlrev_b32_e32 v250, 16, v99
	v_and_b32_e32 v251, 0xffff0000, v99
	v_pk_mul_f32 v[104:105], v[242:243], s[98:99]
	v_pk_mul_f32 v[106:107], v[246:247], s[98:99]
	v_pk_mul_f32 v[108:109], v[248:249], s[98:99]
	v_pk_mul_f32 v[110:111], v[250:251], s[98:99]
	v_exp_f32_e32 v104, v104
	v_exp_f32_e32 v105, v105
	v_exp_f32_e32 v106, v106
	v_exp_f32_e32 v107, v107
	v_exp_f32_e32 v108, v108
	v_exp_f32_e32 v109, v109
	v_exp_f32_e32 v110, v110
	v_exp_f32_e32 v111, v111
	v_pk_add_f32 v[104:105], v[104:105], s[100:101]
	v_pk_add_f32 v[106:107], v[106:107], s[100:101]
	v_pk_add_f32 v[108:109], v[108:109], s[100:101]
	v_pk_add_f32 v[110:111], v[110:111], s[100:101]
	v_rcp_f32_e32 v104, v104
	v_rcp_f32_e32 v105, v105
	v_rcp_f32_e32 v106, v106
	v_rcp_f32_e32 v107, v107
	v_rcp_f32_e32 v108, v108
	v_rcp_f32_e32 v109, v109
	v_rcp_f32_e32 v110, v110
	v_rcp_f32_e32 v111, v111
	v_pk_mul_f32 v[104:105], v[104:105], v[242:243]
	v_pk_mul_f32 v[106:107], v[106:107], v[246:247]
	v_pk_mul_f32 v[108:109], v[108:109], v[248:249]
	v_pk_mul_f32 v[110:111], v[110:111], v[250:251]
	v_lshlrev_b32_e32 v242, 16, v231
	v_and_b32_e32 v243, 0xffff0000, v231
	v_lshlrev_b32_e32 v246, 16, v229
	v_and_b32_e32 v247, 0xffff0000, v229
	v_lshlrev_b32_e32 v248, 16, v232
	v_and_b32_e32 v249, 0xffff0000, v232
	v_lshlrev_b32_e32 v250, 16, v230
	v_and_b32_e32 v251, 0xffff0000, v230
	v_pk_mul_f32 v[242:243], v[242:243], v[170:171] op_sel:[0,1] op_sel_hi:[1,1]
	v_pk_mul_f32 v[246:247], v[246:247], v[170:171] op_sel:[0,1] op_sel_hi:[1,1]
	v_pk_mul_f32 v[248:249], v[248:249], v[170:171] op_sel:[0,1] op_sel_hi:[1,1]
	v_pk_mul_f32 v[250:251], v[250:251], v[170:171] op_sel:[0,1] op_sel_hi:[1,1]
	s_waitcnt lgkmcnt(0)
	v_pk_add_f32 v[242:243], v[242:243], v[124:125]
	v_pk_add_f32 v[246:247], v[246:247], v[126:127]
	v_pk_add_f32 v[248:249], v[248:249], v[128:129]
	v_pk_add_f32 v[250:251], v[250:251], v[130:131]
	v_pk_mul_f32 v[104:105], v[104:105], v[242:243]
	v_pk_mul_f32 v[106:107], v[106:107], v[246:247]
	v_pk_mul_f32 v[108:109], v[108:109], v[248:249]
	v_pk_mul_f32 v[110:111], v[110:111], v[250:251]
	v_mul_f32_e32 v121, v105, v105
	v_fmac_f32_e32 v121, v104, v104
	v_fmac_f32_e32 v121, v106, v106
	v_fmac_f32_e32 v121, v107, v107
	v_fmac_f32_e32 v121, v108, v108
	v_fmac_f32_e32 v121, v109, v109
	v_fmac_f32_e32 v121, v110, v110
	v_fmac_f32_e32 v121, v111, v111
	v_cvt_pk_bf16_f32 v98, v116, v117
	v_cvt_pk_bf16_f32 v97, v114, v115
	v_add_f32_dpp v120, v120, v120 quad_perm:[1,0,3,2] row_mask:0xf bank_mask:0xf
	v_add_f32_dpp v121, v121, v121 quad_perm:[1,0,3,2] row_mask:0xf bank_mask:0xf
	v_cvt_pk_bf16_f32 v96, v112, v113
	v_cvt_pk_bf16_f32 v99, v118, v119
	v_add_f32_dpp v120, v120, v120 quad_perm:[2,3,0,1] row_mask:0xf bank_mask:0xf
	v_add_f32_dpp v121, v121, v121 quad_perm:[2,3,0,1] row_mask:0xf bank_mask:0xf
	global_store_dwordx4 v[180:181], v[96:99], off
	v_cvt_pk_bf16_f32 v100, v104, v105
	v_cvt_pk_bf16_f32 v101, v106, v107
	v_add_f32_dpp v120, v120, v120 row_half_mirror row_mask:0xf bank_mask:0xf
	v_add_f32_dpp v121, v121, v121 row_half_mirror row_mask:0xf bank_mask:0xf
	v_cvt_pk_bf16_f32 v102, v108, v109
	v_cvt_pk_bf16_f32 v103, v110, v111
	v_add_f32_dpp v120, v120, v120 row_mirror row_mask:0xf bank_mask:0xf
	v_add_f32_dpp v121, v121, v121 row_mirror row_mask:0xf bank_mask:0xf
	global_store_dwordx4 v[178:179], v[100:103], off
	s_and_saveexec_b64 s[0:1], s[24:25]
	s_cbranch_execz .LBB0_465
	v_lshl_add_u64 v[96:97], s[66:67], 0, v[172:173]
	v_add_co_u32_e32 v96, vcc, 0x1ec1c000, v96
	s_nop 1
	v_addc_co_u32_e32 v97, vcc, 0, v97, vcc
	global_store_dword v[96:97], v120, off
	global_store_dword v[96:97], v121, off offset:64
	s_branch .LBB0_465
